# attention: gate fragments of both query blocks prefetched at item start (epilogue copies them, no gate loads or waits there); ticket read deferred
# speedup vs baseline: 1.0013x; 1.0013x over previous
.LBB0_499:
	v_lshlrev_b32_e32 v2, 3, v87
	v_lshlrev_b32_e32 v2, 1, v2
	v_lshl_add_u64 v[56:57], s[14:15], 0, v[2:3]
	v_lshl_add_u64 v[64:65], v[56:57], 0, s[18:19]
	v_lshl_add_u64 v[10:11], v[64:65], 0, v[10:11]
	v_mov_b64_e32 v[56:57], v[228:229]
	v_mov_b64_e32 v[58:59], v[230:231]
	v_lshl_add_u64 v[10:11], v[64:65], 0, v[14:15]
	v_mov_b64_e32 v[60:61], v[232:233]
	v_mov_b64_e32 v[62:63], v[234:235]
	v_pk_mul_f32 v[10:11], v[36:37], v[54:55] op_sel_hi:[1,0]
	v_pk_mul_f32 v[14:15], v[38:39], v[54:55] op_sel_hi:[1,0]
	v_pk_mul_f32 v[20:21], v[20:21], v[54:55] op_sel_hi:[1,0]
	v_pk_mul_f32 v[22:23], v[22:23], v[54:55] op_sel_hi:[1,0]
	v_cvt_pk_bf16_f32 v10, v10, v11
	v_cvt_pk_bf16_f32 v11, v14, v15
	v_cvt_pk_bf16_f32 v14, v20, v21
	v_lshl_add_u64 v[20:21], v[64:65], 0, v[52:53]
	v_cvt_pk_bf16_f32 v15, v22, v23
	v_mov_b64_e32 v[20:21], v[236:237]
	v_mov_b64_e32 v[22:23], v[238:239]
	v_pk_mul_f32 v[36:37], v[40:41], v[54:55] op_sel_hi:[1,0]
	v_pk_mul_f32 v[38:39], v[42:43], v[54:55] op_sel_hi:[1,0]
	v_add_u32_e32 v19, 0x1000, v86
	v_pk_mul_f32 v[24:25], v[24:25], v[54:55] op_sel_hi:[1,0]
	v_pk_mul_f32 v[26:27], v[26:27], v[54:55] op_sel_hi:[1,0]
	v_pk_mul_f32 v[40:41], v[44:45], v[54:55] op_sel_hi:[1,0]
	v_pk_mul_f32 v[42:43], v[46:47], v[54:55] op_sel_hi:[1,0]
	v_pk_mul_f32 v[28:29], v[28:29], v[54:55] op_sel_hi:[1,0]
	v_pk_mul_f32 v[30:31], v[30:31], v[54:55] op_sel_hi:[1,0]
	v_pk_mul_f32 v[44:45], v[48:49], v[54:55] op_sel_hi:[1,0]
	v_pk_mul_f32 v[46:47], v[50:51], v[54:55] op_sel_hi:[1,0]
	v_pk_mul_f32 v[32:33], v[32:33], v[54:55] op_sel_hi:[1,0]
	v_pk_mul_f32 v[34:35], v[34:35], v[54:55] op_sel_hi:[1,0]
	v_cvt_pk_bf16_f32 v36, v36, v37
	v_cvt_pk_bf16_f32 v37, v38, v39
	v_cvt_pk_bf16_f32 v24, v24, v25
	v_cvt_pk_bf16_f32 v25, v26, v27
	v_cvt_pk_bf16_f32 v26, v40, v41
	v_cvt_pk_bf16_f32 v27, v42, v43
	v_cvt_pk_bf16_f32 v28, v28, v29
	v_cvt_pk_bf16_f32 v29, v30, v31
	v_cvt_pk_bf16_f32 v30, v44, v45
	v_cvt_pk_bf16_f32 v31, v46, v47
	v_cvt_pk_bf16_f32 v32, v32, v33
	v_cvt_pk_bf16_f32 v33, v34, v35
	ds_write2_b64 v19, v[10:11], v[36:37] offset0:64 offset1:66
	ds_write2_b64 v19, v[14:15], v[24:25] offset0:72 offset1:74
	ds_write2_b64 v19, v[26:27], v[30:31] offset0:68 offset1:70
	ds_write2_b64 v19, v[28:29], v[32:33] offset0:76 offset1:78
	v_lshl_add_u64 v[10:11], v[64:65], 0, v[12:13]
	v_mov_b64_e32 v[10:11], v[240:241]
	v_mov_b64_e32 v[12:13], v[242:243]
	s_waitcnt lgkmcnt(0)
	ds_read_b128 v[24:27], v55 offset:4608
	v_lshl_add_u64 v[14:15], s[24:25], 0, v[2:3]
	v_lshl_add_u64 v[28:29], v[14:15], 0, s[20:21]
	v_lshl_add_u64 v[30:31], v[28:29], 0, v[16:17]
	v_lshl_add_u64 v[4:5], v[28:29], 0, v[4:5]
	s_waitcnt lgkmcnt(0)
	v_lshlrev_b32_e32 v14, 16, v24
	v_and_b32_e32 v15, 0xffff0000, v24
	v_lshlrev_b32_e32 v16, 16, v25
	v_and_b32_e32 v17, 0xffff0000, v25
	v_lshlrev_b32_e32 v24, 16, v26
	v_and_b32_e32 v25, 0xffff0000, v26
	v_lshlrev_b32_e32 v26, 16, v27
	v_and_b32_e32 v27, 0xffff0000, v27
	v_lshl_add_u64 v[8:9], v[28:29], 0, v[8:9]
	v_lshlrev_b32_e32 v32, 16, v56
	v_and_b32_e32 v33, 0xffff0000, v56
	v_lshlrev_b32_e32 v34, 16, v57
	v_and_b32_e32 v35, 0xffff0000, v57
	v_lshlrev_b32_e32 v36, 16, v58
	v_and_b32_e32 v37, 0xffff0000, v58
	v_lshlrev_b32_e32 v38, 16, v59
	v_and_b32_e32 v39, 0xffff0000, v59
	v_pk_mul_f32 v[14:15], v[32:33], v[14:15]
	v_pk_mul_f32 v[16:17], v[34:35], v[16:17]
	v_pk_mul_f32 v[24:25], v[36:37], v[24:25]
	v_pk_mul_f32 v[26:27], v[38:39], v[26:27]
	v_cvt_pk_bf16_f32 v14, v14, v15
	v_cvt_pk_bf16_f32 v15, v16, v17
	v_cvt_pk_bf16_f32 v16, v24, v25
	v_cvt_pk_bf16_f32 v17, v26, v27
	global_store_dwordx4 v[30:31], v[14:17], off sc0 sc1
	s_nop 1
	ds_read_b128 v[14:17], v55 offset:5760
	v_lshlrev_b32_e32 v24, 16, v61
	v_and_b32_e32 v25, 0xffff0000, v61
	v_lshlrev_b32_e32 v26, 16, v62
	v_and_b32_e32 v27, 0xffff0000, v62
	s_waitcnt lgkmcnt(0)
	v_lshlrev_b32_e32 v30, 16, v14
	v_and_b32_e32 v31, 0xffff0000, v14
	v_lshlrev_b32_e32 v14, 16, v15
	v_and_b32_e32 v15, 0xffff0000, v15
	v_lshlrev_b32_e32 v32, 16, v16
	v_and_b32_e32 v33, 0xffff0000, v16
	v_pk_mul_f32 v[24:25], v[24:25], v[14:15]
	v_lshlrev_b32_e32 v40, 16, v60
	v_cvt_pk_bf16_f32 v15, v24, v25
	v_pk_mul_f32 v[24:25], v[26:27], v[32:33]
	v_and_b32_e32 v41, 0xffff0000, v60
	v_cvt_pk_bf16_f32 v16, v24, v25
	v_lshlrev_b32_e32 v24, 16, v17
	v_and_b32_e32 v25, 0xffff0000, v17
	v_lshlrev_b32_e32 v26, 16, v63
	v_and_b32_e32 v27, 0xffff0000, v63
	v_pk_mul_f32 v[30:31], v[40:41], v[30:31]
	v_pk_mul_f32 v[24:25], v[26:27], v[24:25]
	v_cvt_pk_bf16_f32 v14, v30, v31
	v_cvt_pk_bf16_f32 v17, v24, v25
	global_store_dwordx4 v[4:5], v[14:17], off sc0 sc1
	s_nop 1
	ds_read_b128 v[14:17], v55 offset:6912
	v_lshlrev_b32_e32 v24, 16, v20
	v_and_b32_e32 v25, 0xffff0000, v20
	v_lshlrev_b32_e32 v20, 16, v21
	v_and_b32_e32 v21, 0xffff0000, v21
	s_waitcnt lgkmcnt(0)
	v_lshlrev_b32_e32 v4, 16, v14
	v_and_b32_e32 v5, 0xffff0000, v14
	v_pk_mul_f32 v[4:5], v[24:25], v[4:5]
	s_nop 0
	v_cvt_pk_bf16_f32 v14, v4, v5
	v_lshlrev_b32_e32 v4, 16, v15
	v_and_b32_e32 v5, 0xffff0000, v15
	v_pk_mul_f32 v[4:5], v[20:21], v[4:5]
	v_lshlrev_b32_e32 v20, 16, v22
	v_cvt_pk_bf16_f32 v15, v4, v5
	v_lshlrev_b32_e32 v4, 16, v16
	v_and_b32_e32 v5, 0xffff0000, v16
	v_and_b32_e32 v21, 0xffff0000, v22
	v_pk_mul_f32 v[4:5], v[20:21], v[4:5]
	v_lshlrev_b32_e32 v20, 16, v23
	v_cvt_pk_bf16_f32 v16, v4, v5
	v_lshlrev_b32_e32 v4, 16, v17
	v_and_b32_e32 v5, 0xffff0000, v17
	v_and_b32_e32 v21, 0xffff0000, v23
	v_pk_mul_f32 v[4:5], v[20:21], v[4:5]
	s_nop 0
	v_cvt_pk_bf16_f32 v17, v4, v5
	v_lshl_add_u64 v[4:5], v[28:29], 0, v[6:7]
	global_store_dwordx4 v[4:5], v[14:17], off sc0 sc1
	s_nop 1
	ds_read_b128 v[4:7], v55 offset:8064
	v_lshlrev_b32_e32 v16, 16, v10
	v_and_b32_e32 v17, 0xffff0000, v10
	v_lshlrev_b32_e32 v10, 16, v11
	v_and_b32_e32 v11, 0xffff0000, v11
	s_waitcnt lgkmcnt(0)
	v_lshlrev_b32_e32 v14, 16, v4
	v_and_b32_e32 v15, 0xffff0000, v4
	v_pk_mul_f32 v[14:15], v[16:17], v[14:15]
	s_nop 0
	v_cvt_pk_bf16_f32 v4, v14, v15
	v_lshlrev_b32_e32 v14, 16, v5
	v_and_b32_e32 v15, 0xffff0000, v5
	v_pk_mul_f32 v[10:11], v[10:11], v[14:15]
	v_lshlrev_b32_e32 v14, 16, v12
	v_cvt_pk_bf16_f32 v5, v10, v11
	v_lshlrev_b32_e32 v10, 16, v6
	v_and_b32_e32 v11, 0xffff0000, v6
	v_and_b32_e32 v15, 0xffff0000, v12
	v_pk_mul_f32 v[10:11], v[14:15], v[10:11]
	v_lshlrev_b32_e32 v12, 16, v13
	v_cvt_pk_bf16_f32 v6, v10, v11
	v_lshlrev_b32_e32 v10, 16, v7
	v_and_b32_e32 v11, 0xffff0000, v7
	v_and_b32_e32 v13, 0xffff0000, v13
	v_pk_mul_f32 v[10:11], v[12:13], v[10:11]
	s_nop 0
	v_cvt_pk_bf16_f32 v7, v10, v11
	global_store_dwordx4 v[8:9], v[4:7], off sc0 sc1
	s_nop 1

.LBB0_536:
	s_lshl_b32 s68, s25, 6
	s_cmp_lt_i32 s73, 1
	v_and_b32_e32 v188, 31, v186
	s_cbranch_scc1 .LBB0_549
	s_and_b64 s[42:43], s[8:9], exec
	s_cselect_b32 s37, s64, 0x9700000
	v_add_u32_e32 v2, s24, v188
	s_waitcnt lgkmcnt(0)
	s_add_u32 s42, s26, s37
	v_ashrrev_i32_e32 v19, 5, v186
	s_addc_u32 s43, s27, 0
	v_lshlrev_b64 v[4:5], 10, v[2:3]
	v_lshl_add_u64 v[4:5], s[42:43], 0, v[4:5]
	s_lshl_b32 s42, s68, 1
	s_mov_b32 s43, s36
	v_lshlrev_b32_e32 v6, 3, v19
	v_lshl_add_u64 v[4:5], v[4:5], 0, s[42:43]
	v_ashrrev_i32_e32 v7, 31, v6
	s_and_b64 s[42:43], s[14:15], exec
	v_lshl_add_u64 v[20:21], v[6:7], 1, v[4:5]
	s_cselect_b32 s42, 0, 0x8000
	s_mov_b32 s43, s36
	v_lshl_add_u64 v[22:23], v[20:21], 0, s[42:43]
	s_mov_b32 s98, 0xb800000
	s_and_b64 s[100:101], s[8:9], exec
	s_cselect_b32 s98, 0xfa00000, s98
	s_add_u32 s98, s26, s98
	s_addc_u32 s99, s27, 0
	s_lshl_b32 s100, s24, 10
	s_add_u32 s98, s98, s100
	s_addc_u32 s99, s99, 0
	s_lshl_b32 s100, s25, 7
	s_add_u32 s98, s98, s100
	s_addc_u32 s99, s99, 0
	v_lshrrev_b32_e32 v244, 3, v186
	v_and_b32_e32 v245, 7, v186
	v_lshlrev_b32_e32 v244, 10, v244
	v_lshl_or_b32 v244, v245, 4, v244
	v_mov_b32_e32 v245, 0
	v_lshl_add_u64 v[244:245], s[98:99], 0, v[244:245]
	s_mov_b64 s[100:101], 0x2000
	global_load_dwordx4 v[212:215], v[244:245], off
	v_lshl_add_u64 v[244:245], v[244:245], 0, s[100:101]
	global_load_dwordx4 v[216:219], v[244:245], off
	v_lshl_add_u64 v[244:245], v[244:245], 0, s[100:101]
	global_load_dwordx4 v[220:223], v[244:245], off
	v_lshl_add_u64 v[244:245], v[244:245], 0, s[100:101]
	global_load_dwordx4 v[224:227], v[244:245], off
	v_lshl_add_u64 v[244:245], v[244:245], 0, s[100:101]
	global_load_dwordx4 v[228:231], v[244:245], off
	v_lshl_add_u64 v[244:245], v[244:245], 0, s[100:101]
	global_load_dwordx4 v[232:235], v[244:245], off
	v_lshl_add_u64 v[244:245], v[244:245], 0, s[100:101]
	global_load_dwordx4 v[236:239], v[244:245], off
	v_lshl_add_u64 v[244:245], v[244:245], 0, s[100:101]
	global_load_dwordx4 v[240:243], v[244:245], off
	global_load_dwordx4 v[4:7], v[22:23], off offset:96
	global_load_dwordx4 v[8:11], v[22:23], off offset:64
	global_load_dwordx4 v[12:15], v[20:21], off offset:96
	global_load_dwordx4 v[132:135], v[20:21], off offset:64
	global_load_dwordx4 v[136:139], v[22:23], off offset:32
	global_load_dwordx4 v[140:143], v[22:23], off
	global_load_dwordx4 v[144:147], v[20:21], off offset:32
	global_load_dwordx4 v[148:151], v[20:21], off
	s_andn2_b64 vcc, exec, s[40:41]
	s_mov_b64 s[40:41], -1
	s_cbranch_vccnz .LBB0_539
	s_waitcnt vmcnt(0)
	s_mov_b64 s[40:41], 0

.LBB0_576:
	s_mov_b32 s25, s36
	s_waitcnt lgkmcnt(0)
	s_add_u32 s28, s26, s14
	s_addc_u32 s29, s27, s15
	s_lshl_b64 s[14:15], s[24:25], 10
	s_add_u32 s14, s28, s14
	s_addc_u32 s15, s29, s15
	s_lshl_b32 s28, s68, 1
	s_add_u32 s14, s14, s28
	v_ashrrev_i32_e32 v16, 3, v186
	v_and_b32_e32 v87, 7, v186
	s_addc_u32 s15, s15, 0
	v_lshlrev_b32_e32 v2, 4, v87
	v_ashrrev_i32_e32 v17, 31, v16
	v_lshl_add_u64 v[88:89], s[14:15], 0, v[2:3]
	v_lshlrev_b64 v[10:11], 10, v[16:17]
	v_lshl_add_u64 v[6:7], v[88:89], 0, v[10:11]
	v_mov_b64_e32 v[6:7], v[212:213]
	v_mov_b64_e32 v[8:9], v[214:215]
	v_mov_b32_e32 v5, s63
	v_ashrrev_i32_e32 v12, 2, v186
	v_mad_u32_u24 v5, v188, s67, v5
	v_and_b32_e32 v12, -8, v12
	v_add_u32_e32 v86, v5, v12
	v_pk_mul_f32 v[12:13], v[52:53], v[4:5] op_sel_hi:[1,0]
	v_pk_mul_f32 v[14:15], v[54:55], v[4:5] op_sel_hi:[1,0]
	v_cvt_pk_bf16_f32 v12, v12, v13
	v_cvt_pk_bf16_f32 v13, v14, v15
	v_pk_mul_f32 v[14:15], v[68:69], v[4:5] op_sel_hi:[1,0]
	v_add_u32_e32 v90, 8, v16
	v_cvt_pk_bf16_f32 v52, v14, v15
	v_pk_mul_f32 v[14:15], v[70:71], v[4:5] op_sel_hi:[1,0]
	v_ashrrev_i32_e32 v91, 31, v90
	v_cvt_pk_bf16_f32 v53, v14, v15
	v_pk_mul_f32 v[14:15], v[56:57], v[4:5] op_sel_hi:[1,0]
	v_pk_mul_f32 v[68:69], v[58:59], v[4:5] op_sel_hi:[1,0]
	v_cvt_pk_bf16_f32 v54, v14, v15
	v_lshlrev_b64 v[14:15], 10, v[90:91]
	v_lshl_add_u64 v[56:57], v[88:89], 0, v[14:15]
	v_mov_b64_e32 v[56:57], v[216:217]
	v_mov_b64_e32 v[58:59], v[218:219]
	v_cvt_pk_bf16_f32 v55, v68, v69
	ds_write2_b64 v86, v[12:13], v[54:55] offset1:2
	v_pk_mul_f32 v[12:13], v[72:73], v[4:5] op_sel_hi:[1,0]
	v_pk_mul_f32 v[54:55], v[74:75], v[4:5] op_sel_hi:[1,0]
	v_cvt_pk_bf16_f32 v12, v12, v13
	v_cvt_pk_bf16_f32 v13, v54, v55
	ds_write2_b64 v86, v[52:53], v[12:13] offset0:8 offset1:10
	v_pk_mul_f32 v[12:13], v[60:61], v[4:5] op_sel_hi:[1,0]
	v_pk_mul_f32 v[52:53], v[62:63], v[4:5] op_sel_hi:[1,0]
	v_cvt_pk_bf16_f32 v12, v12, v13
	v_cvt_pk_bf16_f32 v13, v52, v53
	v_pk_mul_f32 v[52:53], v[76:77], v[4:5] op_sel_hi:[1,0]
	v_pk_mul_f32 v[54:55], v[78:79], v[4:5] op_sel_hi:[1,0]
	v_cvt_pk_bf16_f32 v52, v52, v53
	v_cvt_pk_bf16_f32 v53, v54, v55
	v_pk_mul_f32 v[54:55], v[64:65], v[4:5] op_sel_hi:[1,0]
	v_pk_mul_f32 v[60:61], v[66:67], v[4:5] op_sel_hi:[1,0]
	v_cvt_pk_bf16_f32 v54, v54, v55
	v_cvt_pk_bf16_f32 v55, v60, v61
	ds_write2_b64 v86, v[12:13], v[54:55] offset0:4 offset1:6
	v_pk_mul_f32 v[12:13], v[80:81], v[4:5] op_sel_hi:[1,0]
	v_pk_mul_f32 v[4:5], v[82:83], v[4:5] op_sel_hi:[1,0]
	v_add_u32_e32 v72, 16, v16
	v_cvt_pk_bf16_f32 v12, v12, v13
	v_cvt_pk_bf16_f32 v13, v4, v5
	v_ashrrev_i32_e32 v73, 31, v72
	ds_write2_b64 v86, v[52:53], v[12:13] offset0:12 offset1:14
	v_lshlrev_b64 v[52:53], 10, v[72:73]
	v_lshl_add_u64 v[4:5], v[88:89], 0, v[52:53]
	v_mov_b64_e32 v[60:61], v[220:221]
	v_mov_b64_e32 v[62:63], v[222:223]
	v_add_u32_e32 v74, 24, v16
	v_ashrrev_i32_e32 v75, 31, v74
	v_lshlrev_b64 v[12:13], 10, v[74:75]
	v_lshl_add_u64 v[4:5], v[88:89], 0, v[12:13]
	v_mov_b64_e32 v[64:65], v[224:225]
	v_mov_b64_e32 v[66:67], v[226:227]
	s_waitcnt lgkmcnt(0)
	v_add_u32_e32 v4, s63, v2
	v_mul_lo_u32 v5, v16, s67
	v_add_u32_e32 v55, v4, v5
	s_lshl_b64 s[24:25], s[24:25], 11
	ds_read_b128 v[68:71], v55
	s_add_u32 s24, s26, s24
	s_addc_u32 s25, s27, s25
	s_lshl_b32 s26, s30, 1
	s_add_u32 s24, s24, s26
	s_addc_u32 s25, s25, 0
	s_add_u32 s24, s24, s28
	s_waitcnt lgkmcnt(0)
	v_lshlrev_b32_e32 v4, 16, v68
	v_and_b32_e32 v5, 0xffff0000, v68
	v_lshlrev_b32_e32 v68, 16, v69
	v_and_b32_e32 v69, 0xffff0000, v69
	s_addc_u32 s25, s25, 0
	s_add_u32 s24, s24, 0x5400000
	s_addc_u32 s25, s25, 0
	v_lshl_add_u64 v[76:77], s[24:25], 0, v[2:3]
	v_lshlrev_b64 v[16:17], 11, v[16:17]
	s_and_b64 vcc, exec, s[6:7]
	v_lshlrev_b32_e32 v78, 16, v6
	v_and_b32_e32 v79, 0xffff0000, v6
	v_lshlrev_b32_e32 v6, 16, v7
	v_and_b32_e32 v7, 0xffff0000, v7
	v_pk_mul_f32 v[4:5], v[78:79], v[4:5]
	v_pk_mul_f32 v[6:7], v[6:7], v[68:69]
	v_cvt_pk_bf16_f32 v4, v4, v5
	v_cvt_pk_bf16_f32 v5, v6, v7
	v_lshlrev_b32_e32 v6, 16, v70
	v_and_b32_e32 v7, 0xffff0000, v70
	v_lshlrev_b32_e32 v68, 16, v8
	v_and_b32_e32 v69, 0xffff0000, v8
	v_pk_mul_f32 v[6:7], v[68:69], v[6:7]
	v_lshlrev_b32_e32 v68, 16, v71
	v_and_b32_e32 v69, 0xffff0000, v71
	v_lshlrev_b32_e32 v8, 16, v9
	v_and_b32_e32 v9, 0xffff0000, v9
	v_pk_mul_f32 v[8:9], v[8:9], v[68:69]
	v_cvt_pk_bf16_f32 v6, v6, v7
	v_cvt_pk_bf16_f32 v7, v8, v9
	v_lshl_add_u64 v[8:9], v[76:77], 0, v[16:17]
	global_store_dwordx4 v[8:9], v[4:7], off sc0 sc1
	s_nop 1
	ds_read_b128 v[4:7], v55 offset:1152
	v_lshlrev_b32_e32 v68, 16, v56
	v_and_b32_e32 v69, 0xffff0000, v56
	s_waitcnt lgkmcnt(0)
	v_lshlrev_b32_e32 v8, 16, v4
	v_and_b32_e32 v9, 0xffff0000, v4
	v_pk_mul_f32 v[8:9], v[68:69], v[8:9]
	v_lshlrev_b32_e32 v4, 16, v5
	v_cvt_pk_bf16_f32 v56, v8, v9
	v_and_b32_e32 v5, 0xffff0000, v5
	v_lshlrev_b32_e32 v8, 16, v57
	v_and_b32_e32 v9, 0xffff0000, v57
	v_pk_mul_f32 v[4:5], v[8:9], v[4:5]
	v_lshlrev_b32_e32 v8, 16, v58
	v_cvt_pk_bf16_f32 v57, v4, v5
	v_lshlrev_b32_e32 v4, 16, v6
	v_and_b32_e32 v5, 0xffff0000, v6
	v_and_b32_e32 v9, 0xffff0000, v58
	v_pk_mul_f32 v[4:5], v[8:9], v[4:5]
	v_lshlrev_b32_e32 v6, 16, v59
	v_cvt_pk_bf16_f32 v58, v4, v5
	v_lshlrev_b32_e32 v4, 16, v7
	v_and_b32_e32 v5, 0xffff0000, v7
	v_and_b32_e32 v7, 0xffff0000, v59
	v_pk_mul_f32 v[4:5], v[6:7], v[4:5]
	s_nop 0
	v_cvt_pk_bf16_f32 v59, v4, v5
	v_lshlrev_b64 v[4:5], 11, v[90:91]
	v_lshl_add_u64 v[6:7], v[76:77], 0, v[4:5]
	global_store_dwordx4 v[6:7], v[56:59], off sc0 sc1
	s_nop 1
	ds_read_b128 v[6:9], v55 offset:2304
	v_lshlrev_b32_e32 v58, 16, v60
	v_and_b32_e32 v59, 0xffff0000, v60
	v_lshlrev_b32_e32 v60, 16, v64
	s_waitcnt lgkmcnt(0)
	v_lshlrev_b32_e32 v56, 16, v6
	v_and_b32_e32 v57, 0xffff0000, v6
	v_pk_mul_f32 v[56:57], v[58:59], v[56:57]
	v_lshlrev_b32_e32 v6, 16, v7
	v_and_b32_e32 v7, 0xffff0000, v7
	v_lshlrev_b32_e32 v58, 16, v61
	v_and_b32_e32 v59, 0xffff0000, v61
	v_pk_mul_f32 v[6:7], v[58:59], v[6:7]
	v_cvt_pk_bf16_f32 v56, v56, v57
	v_cvt_pk_bf16_f32 v57, v6, v7
	v_lshlrev_b32_e32 v6, 16, v8
	v_and_b32_e32 v7, 0xffff0000, v8
	v_lshlrev_b32_e32 v58, 16, v62
	v_and_b32_e32 v59, 0xffff0000, v62
	v_pk_mul_f32 v[6:7], v[58:59], v[6:7]
	v_lshlrev_b32_e32 v8, 16, v63
	v_cvt_pk_bf16_f32 v58, v6, v7
	v_lshlrev_b32_e32 v6, 16, v9
	v_and_b32_e32 v7, 0xffff0000, v9
	v_and_b32_e32 v9, 0xffff0000, v63
	v_pk_mul_f32 v[6:7], v[8:9], v[6:7]
	v_and_b32_e32 v61, 0xffff0000, v64
	v_cvt_pk_bf16_f32 v59, v6, v7
	v_lshlrev_b64 v[6:7], 11, v[72:73]
	v_lshl_add_u64 v[8:9], v[76:77], 0, v[6:7]
	global_store_dwordx4 v[8:9], v[56:59], off sc0 sc1
	s_nop 1
	ds_read_b128 v[56:59], v55 offset:3456
	s_waitcnt lgkmcnt(0)
	v_lshlrev_b32_e32 v8, 16, v56
	v_and_b32_e32 v9, 0xffff0000, v56
	v_pk_mul_f32 v[8:9], v[60:61], v[8:9]
	v_lshlrev_b32_e32 v60, 16, v65
	v_cvt_pk_bf16_f32 v56, v8, v9
	v_lshlrev_b32_e32 v8, 16, v57
	v_and_b32_e32 v9, 0xffff0000, v57
	v_and_b32_e32 v61, 0xffff0000, v65
	v_pk_mul_f32 v[8:9], v[60:61], v[8:9]
	v_lshlrev_b32_e32 v60, 16, v66
	v_cvt_pk_bf16_f32 v57, v8, v9
	v_lshlrev_b32_e32 v8, 16, v58
	v_and_b32_e32 v9, 0xffff0000, v58
	v_and_b32_e32 v61, 0xffff0000, v66
	v_pk_mul_f32 v[8:9], v[60:61], v[8:9]
	v_lshlrev_b32_e32 v60, 16, v67
	v_cvt_pk_bf16_f32 v58, v8, v9
	v_lshlrev_b32_e32 v8, 16, v59
	v_and_b32_e32 v9, 0xffff0000, v59
	v_and_b32_e32 v61, 0xffff0000, v67
	v_pk_mul_f32 v[8:9], v[60:61], v[8:9]
	s_nop 0
	v_cvt_pk_bf16_f32 v59, v8, v9
	v_lshlrev_b64 v[8:9], 11, v[74:75]
	v_lshl_add_u64 v[60:61], v[76:77], 0, v[8:9]
	global_store_dwordx4 v[60:61], v[56:59], off sc0 sc1
	s_nop 1
	s_cbranch_vccnz .LBB0_500
	s_and_b64 vcc, exec, s[8:9]
	s_mov_b64 s[6:7], -1
	s_cbranch_vccnz .LBB0_579
	v_max_f32_e32 v2, v85, v85
	v_max_f32_e32 v54, v19, v19
	v_max_f32_e32 v2, v54, v2
	v_sub_f32_e32 v19, v19, v2
	v_sub_f32_e32 v2, v85, v2
	v_exp_f32_e32 v19, v19
	v_exp_f32_e32 v2, v2
	s_nop 0
	v_fmac_f32_e32 v2, v84, v19
	v_div_scale_f32 v54, s[6:7], v2, v2, v19
	v_rcp_f32_e32 v56, v54
	v_div_scale_f32 v57, vcc, v19, v2, v19
	s_mov_b64 s[6:7], 0
	v_fma_f32 v58, -v54, v56, 1.0
	v_fmac_f32_e32 v56, v58, v56
	v_mul_f32_e32 v58, v57, v56
	v_fma_f32 v59, -v54, v58, v57
	v_fmac_f32_e32 v58, v59, v56
	v_fma_f32 v54, -v54, v58, v57
	v_div_fmas_f32 v54, v54, v56, v58
	v_div_fixup_f32 v54, v54, v2, v19

	.amdhsa_kernel _Z10hybrid_fwd4Args
		.amdhsa_group_segment_fixed_size 0
		.amdhsa_private_segment_fixed_size 0
		.amdhsa_kernarg_size 464
		.amdhsa_user_sgpr_count 2
		.amdhsa_user_sgpr_dispatch_ptr 0
		.amdhsa_user_sgpr_queue_ptr 0
		.amdhsa_user_sgpr_kernarg_segment_ptr 1
		.amdhsa_user_sgpr_dispatch_id 0
		.amdhsa_user_sgpr_kernarg_preload_length 0
		.amdhsa_user_sgpr_kernarg_preload_offset 0
		.amdhsa_user_sgpr_private_segment_size 0
		.amdhsa_uses_dynamic_stack 0
		.amdhsa_enable_private_segment 0
		.amdhsa_system_sgpr_workgroup_id_x 1
		.amdhsa_system_sgpr_workgroup_id_y 0
		.amdhsa_system_sgpr_workgroup_id_z 0
		.amdhsa_system_sgpr_workgroup_info 0
		.amdhsa_system_vgpr_workitem_id 0
		.amdhsa_next_free_vgpr 255
		.amdhsa_next_free_sgpr 102
		.amdhsa_accum_offset 256
		.amdhsa_reserve_vcc 1
		.amdhsa_float_round_mode_32 0
		.amdhsa_float_round_mode_16_64 0
		.amdhsa_float_denorm_mode_32 3
		.amdhsa_float_denorm_mode_16_64 3
		.amdhsa_dx10_clamp 1
		.amdhsa_ieee_mode 1
		.amdhsa_fp16_overflow 0
		.amdhsa_tg_split 0
		.amdhsa_exception_fp_ieee_invalid_op 0
		.amdhsa_exception_fp_denorm_src 0
		.amdhsa_exception_fp_ieee_div_zero 0
		.amdhsa_exception_fp_ieee_overflow 0
		.amdhsa_exception_fp_ieee_underflow 0
		.amdhsa_exception_fp_ieee_inexact 0
		.amdhsa_exception_int_div_zero 0
	.end_amdhsa_kernel

amdhsa.kernels:
  - .agpr_count:     0
    .args:
      - .offset:         0
        .size:           208
        .value_kind:     by_value
      - .offset:         208
        .size:           4
        .value_kind:     hidden_block_count_x
      - .offset:         212
        .size:           4
        .value_kind:     hidden_block_count_y
      - .offset:         216
        .size:           4
        .value_kind:     hidden_block_count_z
      - .offset:         220
        .size:           2
        .value_kind:     hidden_group_size_x
      - .offset:         222
        .size:           2
        .value_kind:     hidden_group_size_y
      - .offset:         224
        .size:           2
        .value_kind:     hidden_group_size_z
      - .offset:         226
        .size:           2
        .value_kind:     hidden_remainder_x
      - .offset:         228
        .size:           2
        .value_kind:     hidden_remainder_y
      - .offset:         230
        .size:           2
        .value_kind:     hidden_remainder_z
      - .offset:         248
        .size:           8
        .value_kind:     hidden_global_offset_x
      - .offset:         256
        .size:           8
        .value_kind:     hidden_global_offset_y
      - .offset:         264
        .size:           8
        .value_kind:     hidden_global_offset_z
      - .offset:         272
        .size:           2
        .value_kind:     hidden_grid_dims
      - .offset:         328
        .size:           4
        .value_kind:     hidden_dynamic_lds_size
    .group_segment_fixed_size: 0
    .kernarg_segment_align: 8
    .kernarg_segment_size: 464
    .language:       OpenCL C
    .language_version:
      - 2
      - 0
    .max_flat_workgroup_size: 512
    .name:           _Z10hybrid_fwd4Args
    .private_segment_fixed_size: 0
    .sgpr_count:     108
    .sgpr_spill_count: 4
    .symbol:         _Z10hybrid_fwd4Args.kd
    .uniform_work_group_size: 1
    .uses_dynamic_stack: false
    .vgpr_count:     255
    .vgpr_spill_count: 0
    .wavefront_size: 64
